# edge attention steps: for blocks T and T-1 (all distances < 128) the 16 bias lookups per column group use one base address plus immediate offsets instead of add/min/shift per value
# baseline (speedup 1.0000x reference)
; __device__ __forceinline__ void logits(float (&v)[4][4], const f32x4 (&s)[4], int tq, int kpos0, int kstride, int fq, int H, const float* btab, float farb, bool use_tab, int wl) {
; #pragma unroll
;     for (int f = 0; f < 4; ++f)
; #pragma unroll
;         for (int i = 0; i < 4; ++i) {
;             const int kk = 32 * (f >> 1) + 8 * fq + 4 * (f & 1) + i;
;             const int dist = tq - (kpos0 + kstride * kk);
;             const bool ok = dist >= 0 && dist < wl;
;             const int di = dist < 0 ? 0 : (dist > 128 ? 128 : dist);
;             v[f][i] = ok ? s[f][i] + btab[di * 16 + H] : -1e30f;
;         }
; }
; template <int CGM> ...
;     float v[2][4][4]; float mnew[2] = {m[0], m[1]};
; #pragma unroll
;     for (int cg_ = 0; cg_ < 2; ++cg_) if ((CGM >> cg_) & 1) {
;         f32x4 s[4]; qk(s, kf, q[cg_], 0.f); logits(v[cg_], s, tq[cg_], key0, 1, fq, H, btab, 0.f, true, wl);
.Lub_edge:
	s_waitcnt lgkmcnt(7)
	v_mfma_f32_16x16x32_bf16 v[150:153], v[78:81], v[2:5], 0
	v_mfma_f32_16x16x32_bf16 v[158:161], v[78:81], v[10:13], 0
	s_waitcnt lgkmcnt(6)
	v_mfma_f32_16x16x32_bf16 v[154:157], v[70:73], v[2:5], 0
	v_mfma_f32_16x16x32_bf16 v[174:177], v[70:73], v[10:13], 0
	s_waitcnt lgkmcnt(5)
	v_mfma_f32_16x16x32_bf16 v[150:153], v[74:77], v[6:9], v[150:153]
	v_mfma_f32_16x16x32_bf16 v[158:161], v[74:77], v[14:17], v[158:161]
	s_waitcnt lgkmcnt(4)
	v_mfma_f32_16x16x32_bf16 v[154:157], v[66:69], v[6:9], v[154:157]
	v_mfma_f32_16x16x32_bf16 v[174:177], v[66:69], v[14:17], v[174:177]
	s_waitcnt lgkmcnt(3)
	v_mfma_f32_16x16x32_bf16 v[98:101], v[62:65], v[2:5], 0
	v_mfma_f32_16x16x32_bf16 v[106:109], v[62:65], v[10:13], 0
	s_waitcnt lgkmcnt(2)
	v_mfma_f32_16x16x32_bf16 v[102:105], v[50:53], v[2:5], 0
	v_mfma_f32_16x16x32_bf16 v[110:113], v[50:53], v[10:13], 0
	s_waitcnt lgkmcnt(1)
	v_mfma_f32_16x16x32_bf16 v[98:101], v[58:61], v[6:9], v[98:101]
	v_mfma_f32_16x16x32_bf16 v[106:109], v[58:61], v[14:17], v[106:109]
	s_waitcnt lgkmcnt(0)
	v_mfma_f32_16x16x32_bf16 v[102:105], v[54:57], v[6:9], v[102:105]
	v_mfma_f32_16x16x32_bf16 v[110:113], v[54:57], v[14:17], v[110:113]
	s_add_i32 s99, s0, -1
	s_cmp_ge_i32 s35, s99
	s_cbranch_scc0 .Lub_edge_cl0
	v_lshl_add_u32 v255, v140, 6, v137
	v_add_u32_e32 v255, 0xfffff640, v255
	ds_read_b32 v232, v255 offset:2496
	ds_read_b32 v233, v255 offset:2432
	ds_read_b32 v234, v255 offset:2368
	ds_read_b32 v235, v255 offset:2304
	ds_read_b32 v236, v255 offset:2240
	ds_read_b32 v237, v255 offset:2176
	ds_read_b32 v238, v255 offset:2112
	ds_read_b32 v239, v255 offset:2048
	ds_read_b32 v240, v255 offset:448
	ds_read_b32 v241, v255 offset:384
	ds_read_b32 v242, v255 offset:320
	ds_read_b32 v243, v255 offset:256
	ds_read_b32 v244, v255 offset:192
	ds_read_b32 v245, v255 offset:128
	ds_read_b32 v246, v255 offset:64
	ds_read_b32 v247, v255 offset:0
	s_branch .Lub_edge_co0
.Lub_edge_cl0:
	v_add_u32_e32 v255, 0, v140
	v_min_u32_e32 v255, 0x80, v255
	v_lshl_add_u32 v232, v255, 6, v137
	ds_read_b32 v232, v232
	v_add_u32_e32 v255, -1, v140
	v_min_u32_e32 v255, 0x80, v255
	v_lshl_add_u32 v233, v255, 6, v137
	ds_read_b32 v233, v233
	v_add_u32_e32 v255, -2, v140
	v_min_u32_e32 v255, 0x80, v255
	v_lshl_add_u32 v234, v255, 6, v137
	ds_read_b32 v234, v234
	v_add_u32_e32 v255, -3, v140
	v_min_u32_e32 v255, 0x80, v255
	v_lshl_add_u32 v235, v255, 6, v137
	ds_read_b32 v235, v235
	v_add_u32_e32 v255, -4, v140
	v_min_u32_e32 v255, 0x80, v255
	v_lshl_add_u32 v236, v255, 6, v137
	ds_read_b32 v236, v236
	v_add_u32_e32 v255, -5, v140
	v_min_u32_e32 v255, 0x80, v255
	v_lshl_add_u32 v237, v255, 6, v137
	ds_read_b32 v237, v237
	v_add_u32_e32 v255, -6, v140
	v_min_u32_e32 v255, 0x80, v255
	v_lshl_add_u32 v238, v255, 6, v137
	ds_read_b32 v238, v238
	v_add_u32_e32 v255, -7, v140
	v_min_u32_e32 v255, 0x80, v255
	v_lshl_add_u32 v239, v255, 6, v137
	ds_read_b32 v239, v239
	v_add_u32_e32 v255, 0xffffffe0, v140
	v_min_u32_e32 v255, 0x80, v255
	v_lshl_add_u32 v240, v255, 6, v137
	ds_read_b32 v240, v240
	v_add_u32_e32 v255, 0xffffffdf, v140
	v_min_u32_e32 v255, 0x80, v255
	v_lshl_add_u32 v241, v255, 6, v137
	ds_read_b32 v241, v241
	v_add_u32_e32 v255, 0xffffffde, v140
	v_min_u32_e32 v255, 0x80, v255
	v_lshl_add_u32 v242, v255, 6, v137
	ds_read_b32 v242, v242
	v_add_u32_e32 v255, 0xffffffdd, v140
	v_min_u32_e32 v255, 0x80, v255
	v_lshl_add_u32 v243, v255, 6, v137
	ds_read_b32 v243, v243
	v_add_u32_e32 v255, 0xffffffdc, v140
	v_min_u32_e32 v255, 0x80, v255
	v_lshl_add_u32 v244, v255, 6, v137
	ds_read_b32 v244, v244
	v_add_u32_e32 v255, 0xffffffdb, v140
	v_min_u32_e32 v255, 0x80, v255
	v_lshl_add_u32 v245, v255, 6, v137
	ds_read_b32 v245, v245
	v_add_u32_e32 v255, 0xffffffda, v140
	v_min_u32_e32 v255, 0x80, v255
	v_lshl_add_u32 v246, v255, 6, v137
	ds_read_b32 v246, v246
	v_add_u32_e32 v255, 0xffffffd9, v140
	v_min_u32_e32 v255, 0x80, v255
	v_lshl_add_u32 v247, v255, 6, v137
	ds_read_b32 v247, v247
.Lub_edge_co0:
	v_add_u32_e32 v248, 0, v140
	v_cmp_gt_u32_e64 s[8:9], s33, v248
	v_add_u32_e32 v249, -1, v140
	v_cmp_gt_u32_e64 s[10:11], s33, v249
	v_add_u32_e32 v250, -2, v140
	v_cmp_gt_u32_e64 s[12:13], s33, v250
	s_waitcnt lgkmcnt(15)
	v_add_f32_e32 v150, v150, v232
	v_cndmask_b32_e64 v150, v148, v150, s[8:9]
	v_add_u32_e32 v248, -3, v140
	v_cmp_gt_u32_e64 s[8:9], s33, v248
	s_waitcnt lgkmcnt(14)
	v_add_f32_e32 v151, v151, v233
	v_cndmask_b32_e64 v151, v148, v151, s[10:11]
	v_add_u32_e32 v249, -4, v140
	v_cmp_gt_u32_e64 s[10:11], s33, v249
	s_waitcnt lgkmcnt(13)
	v_add_f32_e32 v152, v152, v234
	v_cndmask_b32_e64 v152, v148, v152, s[12:13]
	v_add_u32_e32 v250, -5, v140
	v_cmp_gt_u32_e64 s[12:13], s33, v250
	s_waitcnt lgkmcnt(12)
	v_add_f32_e32 v153, v153, v235
	v_cndmask_b32_e64 v153, v148, v153, s[8:9]
	v_add_u32_e32 v248, -6, v140
	v_cmp_gt_u32_e64 s[8:9], s33, v248
	s_waitcnt lgkmcnt(11)
	v_add_f32_e32 v154, v154, v236
	v_cndmask_b32_e64 v154, v148, v154, s[10:11]
	v_add_u32_e32 v249, -7, v140
	v_cmp_gt_u32_e64 s[10:11], s33, v249
	s_waitcnt lgkmcnt(10)
	v_add_f32_e32 v155, v155, v237
	v_cndmask_b32_e64 v155, v148, v155, s[12:13]
	v_add_u32_e32 v250, 0xffffffe0, v140
	v_cmp_gt_u32_e64 s[12:13], s33, v250
	s_waitcnt lgkmcnt(9)
	v_add_f32_e32 v156, v156, v238
	v_cndmask_b32_e64 v156, v148, v156, s[8:9]
	v_add_u32_e32 v248, 0xffffffdf, v140
	v_cmp_gt_u32_e64 s[8:9], s33, v248
	s_waitcnt lgkmcnt(8)
	v_add_f32_e32 v157, v157, v239
	v_cndmask_b32_e64 v157, v148, v157, s[10:11]
	v_add_u32_e32 v249, 0xffffffde, v140
	v_cmp_gt_u32_e64 s[10:11], s33, v249
	s_waitcnt lgkmcnt(7)
	v_add_f32_e32 v98, v98, v240
	v_cndmask_b32_e64 v98, v148, v98, s[12:13]
	v_add_u32_e32 v250, 0xffffffdd, v140
	v_cmp_gt_u32_e64 s[12:13], s33, v250
	s_waitcnt lgkmcnt(6)
	v_add_f32_e32 v99, v99, v241
	v_cndmask_b32_e64 v99, v148, v99, s[8:9]
	v_add_u32_e32 v248, 0xffffffdc, v140
	v_cmp_gt_u32_e64 s[8:9], s33, v248
	s_waitcnt lgkmcnt(5)
	v_add_f32_e32 v100, v100, v242
	v_cndmask_b32_e64 v100, v148, v100, s[10:11]
	v_add_u32_e32 v249, 0xffffffdb, v140
	v_cmp_gt_u32_e64 s[10:11], s33, v249
	s_waitcnt lgkmcnt(4)
	v_add_f32_e32 v101, v101, v243
	v_cndmask_b32_e64 v101, v148, v101, s[12:13]
	v_add_u32_e32 v250, 0xffffffda, v140
	v_cmp_gt_u32_e64 s[12:13], s33, v250
	s_waitcnt lgkmcnt(3)
	v_add_f32_e32 v102, v102, v244
	v_cndmask_b32_e64 v102, v148, v102, s[8:9]
	v_add_u32_e32 v248, 0xffffffd9, v140
	v_cmp_gt_u32_e64 s[8:9], s33, v248
	s_waitcnt lgkmcnt(2)
	v_add_f32_e32 v103, v103, v245
	v_cndmask_b32_e64 v103, v148, v103, s[10:11]
	s_waitcnt lgkmcnt(1)
	v_add_f32_e32 v104, v104, v246
	v_cndmask_b32_e64 v104, v148, v104, s[12:13]
	s_waitcnt lgkmcnt(0)
	v_add_f32_e32 v105, v105, v247
	v_cndmask_b32_e64 v105, v148, v105, s[8:9]
	s_add_i32 s99, s0, -1
	s_cmp_ge_i32 s35, s99
	s_cbranch_scc0 .Lub_edge_cl1
; __device__ __forceinline__ void logits(float (&v)[4][4], const f32x4 (&s)[4], int tq, int kpos0, int kstride, int fq, int H, const float* btab, float farb, bool use_tab, int wl) {
; #pragma unroll
;     for (int f = 0; f < 4; ++f)
; #pragma unroll
;         for (int i = 0; i < 4; ++i) {
;             const int kk = 32 * (f >> 1) + 8 * fq + 4 * (f & 1) + i;
;             const int dist = tq - (kpos0 + kstride * kk);
;             const bool ok = dist >= 0 && dist < wl;
;             const int di = dist < 0 ? 0 : (dist > 128 ? 128 : dist);
;             v[f][i] = ok ? s[f][i] + btab[di * 16 + H] : -1e30f;
;         }
; }
	v_lshl_add_u32 v255, v140, 6, v137
	v_add_u32_e32 v255, 0xfffff740, v255
	ds_read_b32 v232, v255 offset:2496
	ds_read_b32 v233, v255 offset:2432
	ds_read_b32 v234, v255 offset:2368
	ds_read_b32 v235, v255 offset:2304
	ds_read_b32 v236, v255 offset:2240
	ds_read_b32 v237, v255 offset:2176
	ds_read_b32 v238, v255 offset:2112
	ds_read_b32 v239, v255 offset:2048
	ds_read_b32 v240, v255 offset:448
	ds_read_b32 v241, v255 offset:384
	ds_read_b32 v242, v255 offset:320
	ds_read_b32 v243, v255 offset:256
	ds_read_b32 v244, v255 offset:192
	ds_read_b32 v245, v255 offset:128
	ds_read_b32 v246, v255 offset:64
	ds_read_b32 v247, v255 offset:0
	s_branch .Lub_edge_co1
.Lub_edge_cl1:
	v_add_u32_e32 v255, 4, v140
	v_min_u32_e32 v255, 0x80, v255
	v_lshl_add_u32 v232, v255, 6, v137
	ds_read_b32 v232, v232
	v_add_u32_e32 v255, 3, v140
	v_min_u32_e32 v255, 0x80, v255
	v_lshl_add_u32 v233, v255, 6, v137
	ds_read_b32 v233, v233
	v_add_u32_e32 v255, 2, v140
	v_min_u32_e32 v255, 0x80, v255
	v_lshl_add_u32 v234, v255, 6, v137
	ds_read_b32 v234, v234
	v_add_u32_e32 v255, 1, v140
	v_min_u32_e32 v255, 0x80, v255
	v_lshl_add_u32 v235, v255, 6, v137
	ds_read_b32 v235, v235
	v_add_u32_e32 v255, 0, v140
	v_min_u32_e32 v255, 0x80, v255
	v_lshl_add_u32 v236, v255, 6, v137
	ds_read_b32 v236, v236
	v_add_u32_e32 v255, -1, v140
	v_min_u32_e32 v255, 0x80, v255
	v_lshl_add_u32 v237, v255, 6, v137
	ds_read_b32 v237, v237
	v_add_u32_e32 v255, -2, v140
	v_min_u32_e32 v255, 0x80, v255
	v_lshl_add_u32 v238, v255, 6, v137
	ds_read_b32 v238, v238
	v_add_u32_e32 v255, -3, v140
	v_min_u32_e32 v255, 0x80, v255
	v_lshl_add_u32 v239, v255, 6, v137
	ds_read_b32 v239, v239
	v_add_u32_e32 v255, 0xffffffe4, v140
	v_min_u32_e32 v255, 0x80, v255
	v_lshl_add_u32 v240, v255, 6, v137
	ds_read_b32 v240, v240
	v_add_u32_e32 v255, 0xffffffe3, v140
	v_min_u32_e32 v255, 0x80, v255
	v_lshl_add_u32 v241, v255, 6, v137
	ds_read_b32 v241, v241
	v_add_u32_e32 v255, 0xffffffe2, v140
	v_min_u32_e32 v255, 0x80, v255
	v_lshl_add_u32 v242, v255, 6, v137
	ds_read_b32 v242, v242
	v_add_u32_e32 v255, 0xffffffe1, v140
	v_min_u32_e32 v255, 0x80, v255
	v_lshl_add_u32 v243, v255, 6, v137
	ds_read_b32 v243, v243
	v_add_u32_e32 v255, 0xffffffe0, v140
	v_min_u32_e32 v255, 0x80, v255
	v_lshl_add_u32 v244, v255, 6, v137
	ds_read_b32 v244, v244
	v_add_u32_e32 v255, 0xffffffdf, v140
	v_min_u32_e32 v255, 0x80, v255
	v_lshl_add_u32 v245, v255, 6, v137
	ds_read_b32 v245, v245
	v_add_u32_e32 v255, 0xffffffde, v140
	v_min_u32_e32 v255, 0x80, v255
	v_lshl_add_u32 v246, v255, 6, v137
	ds_read_b32 v246, v246
	v_add_u32_e32 v255, 0xffffffdd, v140
	v_min_u32_e32 v255, 0x80, v255
	v_lshl_add_u32 v247, v255, 6, v137
	ds_read_b32 v247, v247
; __device__ __forceinline__ void logits(float (&v)[4][4], const f32x4 (&s)[4], int tq, int kpos0, int kstride, int fq, int H, const float* btab, float farb, bool use_tab, int wl) {
; #pragma unroll
;     for (int f = 0; f < 4; ++f)
; #pragma unroll
;         for (int i = 0; i < 4; ++i) {
;             const int kk = 32 * (f >> 1) + 8 * fq + 4 * (f & 1) + i;
;             const int dist = tq - (kpos0 + kstride * kk);
;             const bool ok = dist >= 0 && dist < wl;
;             const int di = dist < 0 ? 0 : (dist > 128 ? 128 : dist);
;             v[f][i] = ok ? s[f][i] + btab[di * 16 + H] : -1e30f;
;         }
; }
; template <int CGM> ...
;     ...
;         f32x4 s[4]; qk(s, kf, q[cg_], 0.f); logits(v[cg_], s, tq[cg_], key0, 1, fq, H, btab, 0.f, true, wl);
;         float mx = red_max4(max16(v[cg_])); if (!selq[cg_]) mx = -1e30f; mnew[cg_] = fmaxf(m[cg_], mx);
;     }
;     if (__any(mnew[0] > m[0] || mnew[1] > m[1])) {
; #pragma unroll
;         for (int cg_ = 0; cg_ < 2; ++cg_) if ((CGM >> cg_) & 1) {
;             const float sc = __builtin_amdgcn_exp2f(m[cg_] - mnew[cg_]); l[cg_] *= sc; m[cg_] = mnew[cg_];
; #pragma unroll
;             for (int df = 0; df < 4; ++df) o[cg_][df] *= sc;
;         }
.Lub_edge_co1:
	v_add_u32_e32 v248, 4, v140
	v_cmp_gt_u32_e64 s[8:9], s33, v248
	v_add_u32_e32 v249, 3, v140
	v_cmp_gt_u32_e64 s[10:11], s33, v249
	v_add_u32_e32 v250, 2, v140
	v_cmp_gt_u32_e64 s[12:13], s33, v250
	s_waitcnt lgkmcnt(15)
	v_add_f32_e32 v158, v158, v232
	v_cndmask_b32_e64 v158, v148, v158, s[8:9]
	v_add_u32_e32 v248, 1, v140
	v_cmp_gt_u32_e64 s[8:9], s33, v248
	s_waitcnt lgkmcnt(14)
	v_add_f32_e32 v159, v159, v233
	v_cndmask_b32_e64 v159, v148, v159, s[10:11]
	v_add_u32_e32 v249, 0, v140
	v_cmp_gt_u32_e64 s[10:11], s33, v249
	s_waitcnt lgkmcnt(13)
	v_add_f32_e32 v160, v160, v234
	v_cndmask_b32_e64 v160, v148, v160, s[12:13]
	v_add_u32_e32 v250, -1, v140
	v_cmp_gt_u32_e64 s[12:13], s33, v250
	s_waitcnt lgkmcnt(12)
	v_add_f32_e32 v161, v161, v235
	v_cndmask_b32_e64 v161, v148, v161, s[8:9]
	v_add_u32_e32 v248, -2, v140
	v_cmp_gt_u32_e64 s[8:9], s33, v248
	s_waitcnt lgkmcnt(11)
	v_add_f32_e32 v174, v174, v236
	v_cndmask_b32_e64 v174, v148, v174, s[10:11]
	v_add_u32_e32 v249, -3, v140
	v_cmp_gt_u32_e64 s[10:11], s33, v249
	s_waitcnt lgkmcnt(10)
	v_add_f32_e32 v175, v175, v237
	v_cndmask_b32_e64 v175, v148, v175, s[12:13]
	v_add_u32_e32 v250, 0xffffffe4, v140
	v_cmp_gt_u32_e64 s[12:13], s33, v250
	s_waitcnt lgkmcnt(9)
	v_add_f32_e32 v176, v176, v238
	v_cndmask_b32_e64 v176, v148, v176, s[8:9]
	v_add_u32_e32 v248, 0xffffffe3, v140
	v_cmp_gt_u32_e64 s[8:9], s33, v248
	s_waitcnt lgkmcnt(8)
	v_add_f32_e32 v177, v177, v239
	v_cndmask_b32_e64 v177, v148, v177, s[10:11]
	v_add_u32_e32 v249, 0xffffffe2, v140
	v_cmp_gt_u32_e64 s[10:11], s33, v249
	s_waitcnt lgkmcnt(7)
	v_add_f32_e32 v106, v106, v240
	v_cndmask_b32_e64 v106, v148, v106, s[12:13]
	v_add_u32_e32 v250, 0xffffffe1, v140
	v_cmp_gt_u32_e64 s[12:13], s33, v250
	s_waitcnt lgkmcnt(6)
	v_add_f32_e32 v107, v107, v241
	v_cndmask_b32_e64 v107, v148, v107, s[8:9]
	v_add_u32_e32 v248, 0xffffffe0, v140
	v_cmp_gt_u32_e64 s[8:9], s33, v248
	s_waitcnt lgkmcnt(5)
	v_add_f32_e32 v108, v108, v242
	v_cndmask_b32_e64 v108, v148, v108, s[10:11]
	v_add_u32_e32 v249, 0xffffffdf, v140
	v_cmp_gt_u32_e64 s[10:11], s33, v249
	s_waitcnt lgkmcnt(4)
	v_add_f32_e32 v109, v109, v243
	v_cndmask_b32_e64 v109, v148, v109, s[12:13]
	v_add_u32_e32 v250, 0xffffffde, v140
	v_cmp_gt_u32_e64 s[12:13], s33, v250
	s_waitcnt lgkmcnt(3)
	v_add_f32_e32 v110, v110, v244
	v_cndmask_b32_e64 v110, v148, v110, s[8:9]
	v_add_u32_e32 v248, 0xffffffdd, v140
	v_cmp_gt_u32_e64 s[8:9], s33, v248
	s_waitcnt lgkmcnt(2)
	v_add_f32_e32 v111, v111, v245
	v_cndmask_b32_e64 v111, v148, v111, s[10:11]
	s_waitcnt lgkmcnt(1)
	v_add_f32_e32 v112, v112, v246
	v_cndmask_b32_e64 v112, v148, v112, s[12:13]
	s_waitcnt lgkmcnt(0)
	v_add_f32_e32 v113, v113, v247
	v_cndmask_b32_e64 v113, v148, v113, s[8:9]
	ds_read_b128 v[78:81], v143 offset:8192
	ds_read_b128 v[70:73], v143 offset:8704
	ds_read_b128 v[62:65], v143 offset:12288
	ds_read_b128 v[50:53], v143 offset:12800
	ds_read_b128 v[74:77], v142 offset:8192
	ds_read_b128 v[66:69], v142 offset:8704
	ds_read_b128 v[58:61], v142 offset:12288
	ds_read_b128 v[54:57], v142 offset:12800
	v_max3_f32 v144, v150, v151, v152
	v_max3_f32 v145, v153, v154, v155
	v_max3_f32 v146, v156, v157, v98
	v_max3_f32 v147, v99, v100, v101
	v_max3_f32 v178, v158, v159, v160
	v_max3_f32 v179, v161, v174, v175
	v_max3_f32 v180, v176, v177, v106
	v_max3_f32 v181, v107, v108, v109
	v_max3_f32 v144, v144, v102, v103
	v_max3_f32 v145, v145, v104, v105
	v_max3_f32 v178, v178, v110, v111
	v_max3_f32 v179, v179, v112, v113
	v_max3_f32 v144, v144, v145, v146
	v_max3_f32 v178, v178, v179, v180
	v_max_f32_e32 v144, v144, v147
	v_max_f32_e32 v178, v178, v181
	v_mov_b32_e32 v145, v144
	v_mov_b32_e32 v179, v178
	s_nop 1
	v_permlane16_swap_b32_e32 v144, v145
	v_permlane16_swap_b32_e32 v178, v179
	v_max_f32_e32 v144, v144, v145
	v_max_f32_e32 v178, v178, v179
	v_mov_b32_e32 v145, v144
	v_mov_b32_e32 v179, v178
	s_nop 1
	v_permlane32_swap_b32_e32 v144, v145
	v_permlane32_swap_b32_e32 v178, v179
	v_max_f32_e32 v144, v144, v145
	v_max_f32_e32 v178, v178, v179
	v_max_f32_e32 v145, v122, v144
	v_max_f32_e32 v179, v123, v178
	v_cmp_gt_f32_e32 vcc, v145, v122
	v_cmp_gt_f32_e64 s[8:9], v179, v123
	s_or_b64 vcc, vcc, s[8:9]
	s_cbranch_vccz .Lub_edge_nors
	v_sub_f32_e32 v144, v122, v145
	v_sub_f32_e32 v180, v123, v179
	v_exp_f32_e32 v144, v144
	v_exp_f32_e32 v180, v180
	v_mov_b32_e32 v122, v145
	v_mov_b32_e32 v123, v179
	v_mul_f32_e32 v124, v124, v144
	v_pk_mul_f32 v[46:47], v[46:47], v[144:145] op_sel_hi:[1,0]
	v_pk_mul_f32 v[48:49], v[48:49], v[144:145] op_sel_hi:[1,0]
	v_pk_mul_f32 v[38:39], v[38:39], v[144:145] op_sel_hi:[1,0]
	v_pk_mul_f32 v[40:41], v[40:41], v[144:145] op_sel_hi:[1,0]
	v_pk_mul_f32 v[30:31], v[30:31], v[144:145] op_sel_hi:[1,0]
	v_pk_mul_f32 v[32:33], v[32:33], v[144:145] op_sel_hi:[1,0]
	v_pk_mul_f32 v[22:23], v[22:23], v[144:145] op_sel_hi:[1,0]
	v_pk_mul_f32 v[24:25], v[24:25], v[144:145] op_sel_hi:[1,0]
	v_mul_f32_e32 v125, v125, v180
	v_pk_mul_f32 v[42:43], v[42:43], v[180:181] op_sel_hi:[1,0]
	v_pk_mul_f32 v[44:45], v[44:45], v[180:181] op_sel_hi:[1,0]
	v_pk_mul_f32 v[34:35], v[34:35], v[180:181] op_sel_hi:[1,0]
	v_pk_mul_f32 v[36:37], v[36:37], v[180:181] op_sel_hi:[1,0]
	v_pk_mul_f32 v[26:27], v[26:27], v[180:181] op_sel_hi:[1,0]
	v_pk_mul_f32 v[28:29], v[28:29], v[180:181] op_sel_hi:[1,0]
	v_pk_mul_f32 v[18:19], v[18:19], v[180:181] op_sel_hi:[1,0]
	v_pk_mul_f32 v[20:21], v[20:21], v[180:181] op_sel_hi:[1,0]

; __device__ __forceinline__ void logits(float (&v)[4][4], const f32x4 (&s)[4], int tq, int kpos0, int kstride, int fq, int H, const float* btab, float farb, bool use_tab, int wl) {
; #pragma unroll
;     for (int f = 0; f < 4; ++f)
; #pragma unroll
;         for (int i = 0; i < 4; ++i) {
;             const int kk = 32 * (f >> 1) + 8 * fq + 4 * (f & 1) + i;
;             const int dist = tq - (kpos0 + kstride * kk);
;             const bool ok = dist >= 0 && dist < wl;
;             const int di = dist < 0 ? 0 : (dist > 128 ? 128 : dist);
;             v[f][i] = ok ? s[f][i] + btab[di * 16 + H] : -1e30f;
;         }
; }
; template <int CGM> ...
;     float v[2][4][4]; float mnew[2] = {m[0], m[1]};
; #pragma unroll
;     for (int cg_ = 0; cg_ < 2; ++cg_) if ((CGM >> cg_) & 1) {
;         f32x4 s[4]; qk(s, kf, q[cg_], 0.f); logits(v[cg_], s, tq[cg_], key0, 1, fq, H, btab, 0.f, true, wl);
.Lsel_edge:
	s_mov_b32 s98, 0x40000000
	v_add_u32_e32 v251, s4, v141
	s_waitcnt lgkmcnt(7)
	v_mfma_f32_16x16x32_bf16 v[92:95], v[88:91], v[2:5], 0
	v_mfma_f32_16x16x32_bf16 v[108:111], v[88:91], v[10:13], 0
	s_waitcnt lgkmcnt(6)
	v_mfma_f32_16x16x32_bf16 v[96:99], v[80:83], v[2:5], 0
	v_mfma_f32_16x16x32_bf16 v[112:115], v[80:83], v[10:13], 0
	s_waitcnt lgkmcnt(5)
	v_mfma_f32_16x16x32_bf16 v[92:95], v[84:87], v[6:9], v[92:95]
	v_mfma_f32_16x16x32_bf16 v[108:111], v[84:87], v[14:17], v[108:111]
	s_waitcnt lgkmcnt(4)
	v_mfma_f32_16x16x32_bf16 v[96:99], v[76:79], v[6:9], v[96:99]
	v_mfma_f32_16x16x32_bf16 v[112:115], v[76:79], v[14:17], v[112:115]
	s_waitcnt lgkmcnt(3)
	v_mfma_f32_16x16x32_bf16 v[100:103], v[72:75], v[2:5], 0
	v_mfma_f32_16x16x32_bf16 v[116:119], v[72:75], v[10:13], 0
	s_waitcnt lgkmcnt(2)
	v_mfma_f32_16x16x32_bf16 v[104:107], v[60:63], v[2:5], 0
	v_mfma_f32_16x16x32_bf16 v[120:123], v[60:63], v[10:13], 0
	s_waitcnt lgkmcnt(1)
	v_mfma_f32_16x16x32_bf16 v[100:103], v[68:71], v[6:9], v[100:103]
	v_mfma_f32_16x16x32_bf16 v[116:119], v[68:71], v[14:17], v[116:119]
	s_waitcnt lgkmcnt(0)
	v_mfma_f32_16x16x32_bf16 v[104:107], v[64:67], v[6:9], v[104:107]
	v_mfma_f32_16x16x32_bf16 v[120:123], v[64:67], v[14:17], v[120:123]
	s_add_i32 s99, s0, -1
	s_cmp_ge_i32 s48, s99
	s_cbranch_scc0 .Lsel_edge_cl0
	v_lshl_add_u32 v255, v251, 6, v177
	v_add_u32_e32 v255, 0xfffff640, v255
	ds_read_b32 v232, v255 offset:2496
	ds_read_b32 v233, v255 offset:2432
	ds_read_b32 v234, v255 offset:2368
	ds_read_b32 v235, v255 offset:2304
	ds_read_b32 v236, v255 offset:2240
	ds_read_b32 v237, v255 offset:2176
	ds_read_b32 v238, v255 offset:2112
	ds_read_b32 v239, v255 offset:2048
	ds_read_b32 v240, v255 offset:448
	ds_read_b32 v241, v255 offset:384
	ds_read_b32 v242, v255 offset:320
	ds_read_b32 v243, v255 offset:256
	ds_read_b32 v244, v255 offset:192
	ds_read_b32 v245, v255 offset:128
	ds_read_b32 v246, v255 offset:64
	ds_read_b32 v247, v255 offset:0
	s_branch .Lsel_edge_co0
.Lsel_edge_cl0:
	v_add_u32_e32 v255, 0, v251
	v_min_u32_e32 v255, 0x80, v255
	v_lshl_add_u32 v232, v255, 6, v177
	ds_read_b32 v232, v232
	v_add_u32_e32 v255, -1, v251
	v_min_u32_e32 v255, 0x80, v255
	v_lshl_add_u32 v233, v255, 6, v177
	ds_read_b32 v233, v233
	v_add_u32_e32 v255, -2, v251
	v_min_u32_e32 v255, 0x80, v255
	v_lshl_add_u32 v234, v255, 6, v177
	ds_read_b32 v234, v234
	v_add_u32_e32 v255, -3, v251
	v_min_u32_e32 v255, 0x80, v255
	v_lshl_add_u32 v235, v255, 6, v177
	ds_read_b32 v235, v235
	v_add_u32_e32 v255, -4, v251
	v_min_u32_e32 v255, 0x80, v255
	v_lshl_add_u32 v236, v255, 6, v177
	ds_read_b32 v236, v236
	v_add_u32_e32 v255, -5, v251
	v_min_u32_e32 v255, 0x80, v255
	v_lshl_add_u32 v237, v255, 6, v177
	ds_read_b32 v237, v237
	v_add_u32_e32 v255, -6, v251
	v_min_u32_e32 v255, 0x80, v255
	v_lshl_add_u32 v238, v255, 6, v177
	ds_read_b32 v238, v238
	v_add_u32_e32 v255, -7, v251
	v_min_u32_e32 v255, 0x80, v255
	v_lshl_add_u32 v239, v255, 6, v177
	ds_read_b32 v239, v239
	v_add_u32_e32 v255, 0xffffffe0, v251
	v_min_u32_e32 v255, 0x80, v255
	v_lshl_add_u32 v240, v255, 6, v177
	ds_read_b32 v240, v240
	v_add_u32_e32 v255, 0xffffffdf, v251
	v_min_u32_e32 v255, 0x80, v255
	v_lshl_add_u32 v241, v255, 6, v177
	ds_read_b32 v241, v241
	v_add_u32_e32 v255, 0xffffffde, v251
	v_min_u32_e32 v255, 0x80, v255
	v_lshl_add_u32 v242, v255, 6, v177
	ds_read_b32 v242, v242
	v_add_u32_e32 v255, 0xffffffdd, v251
	v_min_u32_e32 v255, 0x80, v255
	v_lshl_add_u32 v243, v255, 6, v177
	ds_read_b32 v243, v243
	v_add_u32_e32 v255, 0xffffffdc, v251
	v_min_u32_e32 v255, 0x80, v255
	v_lshl_add_u32 v244, v255, 6, v177
	ds_read_b32 v244, v244
	v_add_u32_e32 v255, 0xffffffdb, v251
	v_min_u32_e32 v255, 0x80, v255
	v_lshl_add_u32 v245, v255, 6, v177
	ds_read_b32 v245, v245
	v_add_u32_e32 v255, 0xffffffda, v251
	v_min_u32_e32 v255, 0x80, v255
	v_lshl_add_u32 v246, v255, 6, v177
	ds_read_b32 v246, v246
	v_add_u32_e32 v255, 0xffffffd9, v251
	v_min_u32_e32 v255, 0x80, v255
	v_lshl_add_u32 v247, v255, 6, v177
	ds_read_b32 v247, v247
.Lsel_edge_co0:
	v_add_u32_e32 v248, 0, v251
	v_cmp_gt_u32_e64 s[6:7], s98, v248
	v_add_u32_e32 v249, -1, v251
	v_cmp_gt_u32_e64 s[12:13], s98, v249
	v_add_u32_e32 v250, -2, v251
	v_cmp_gt_u32_e64 s[14:15], s98, v250
	s_waitcnt lgkmcnt(15)
	v_add_f32_e32 v92, v92, v232
	v_cndmask_b32_e64 v92, v148, v92, s[6:7]
	v_add_u32_e32 v248, -3, v251
	v_cmp_gt_u32_e64 s[6:7], s98, v248
	s_waitcnt lgkmcnt(14)
	v_add_f32_e32 v93, v93, v233
	v_cndmask_b32_e64 v93, v148, v93, s[12:13]
	v_add_u32_e32 v249, -4, v251
	v_cmp_gt_u32_e64 s[12:13], s98, v249
	s_waitcnt lgkmcnt(13)
	v_add_f32_e32 v94, v94, v234
	v_cndmask_b32_e64 v94, v148, v94, s[14:15]
	v_add_u32_e32 v250, -5, v251
	v_cmp_gt_u32_e64 s[14:15], s98, v250
	s_waitcnt lgkmcnt(12)
	v_add_f32_e32 v95, v95, v235
	v_cndmask_b32_e64 v95, v148, v95, s[6:7]
	v_add_u32_e32 v248, -6, v251
	v_cmp_gt_u32_e64 s[6:7], s98, v248
	s_waitcnt lgkmcnt(11)
	v_add_f32_e32 v96, v96, v236
	v_cndmask_b32_e64 v96, v148, v96, s[12:13]
	v_add_u32_e32 v249, -7, v251
	v_cmp_gt_u32_e64 s[12:13], s98, v249
	s_waitcnt lgkmcnt(10)
	v_add_f32_e32 v97, v97, v237
	v_cndmask_b32_e64 v97, v148, v97, s[14:15]
	v_add_u32_e32 v250, 0xffffffe0, v251
	v_cmp_gt_u32_e64 s[14:15], s98, v250
	s_waitcnt lgkmcnt(9)
	v_add_f32_e32 v98, v98, v238
	v_cndmask_b32_e64 v98, v148, v98, s[6:7]
	v_add_u32_e32 v248, 0xffffffdf, v251
	v_cmp_gt_u32_e64 s[6:7], s98, v248
	s_waitcnt lgkmcnt(8)
	v_add_f32_e32 v99, v99, v239
	v_cndmask_b32_e64 v99, v148, v99, s[12:13]
	v_add_u32_e32 v249, 0xffffffde, v251
	v_cmp_gt_u32_e64 s[12:13], s98, v249
	s_waitcnt lgkmcnt(7)
	v_add_f32_e32 v100, v100, v240
	v_cndmask_b32_e64 v100, v148, v100, s[14:15]
	v_add_u32_e32 v250, 0xffffffdd, v251
	v_cmp_gt_u32_e64 s[14:15], s98, v250
	s_waitcnt lgkmcnt(6)
	v_add_f32_e32 v101, v101, v241
	v_cndmask_b32_e64 v101, v148, v101, s[6:7]
	v_add_u32_e32 v248, 0xffffffdc, v251
	v_cmp_gt_u32_e64 s[6:7], s98, v248
	s_waitcnt lgkmcnt(5)
	v_add_f32_e32 v102, v102, v242
	v_cndmask_b32_e64 v102, v148, v102, s[12:13]
	v_add_u32_e32 v249, 0xffffffdb, v251
	v_cmp_gt_u32_e64 s[12:13], s98, v249
	s_waitcnt lgkmcnt(4)
	v_add_f32_e32 v103, v103, v243
	v_cndmask_b32_e64 v103, v148, v103, s[14:15]
	v_add_u32_e32 v250, 0xffffffda, v251
	v_cmp_gt_u32_e64 s[14:15], s98, v250
	s_waitcnt lgkmcnt(3)
	v_add_f32_e32 v104, v104, v244
	v_cndmask_b32_e64 v104, v148, v104, s[6:7]
	v_add_u32_e32 v248, 0xffffffd9, v251
	v_cmp_gt_u32_e64 s[6:7], s98, v248
	s_waitcnt lgkmcnt(2)
	v_add_f32_e32 v105, v105, v245
	v_cndmask_b32_e64 v105, v148, v105, s[12:13]
	s_waitcnt lgkmcnt(1)
	v_add_f32_e32 v106, v106, v246
	v_cndmask_b32_e64 v106, v148, v106, s[14:15]
	s_waitcnt lgkmcnt(0)
	v_add_f32_e32 v107, v107, v247
	v_cndmask_b32_e64 v107, v148, v107, s[6:7]
	s_add_i32 s99, s0, -1
	s_cmp_ge_i32 s48, s99
	s_cbranch_scc0 .Lsel_edge_cl1
; __device__ __forceinline__ void logits(float (&v)[4][4], const f32x4 (&s)[4], int tq, int kpos0, int kstride, int fq, int H, const float* btab, float farb, bool use_tab, int wl) {
; #pragma unroll
;     for (int f = 0; f < 4; ++f)
; #pragma unroll
;         for (int i = 0; i < 4; ++i) {
;             const int kk = 32 * (f >> 1) + 8 * fq + 4 * (f & 1) + i;
;             const int dist = tq - (kpos0 + kstride * kk);
;             const bool ok = dist >= 0 && dist < wl;
;             const int di = dist < 0 ? 0 : (dist > 128 ? 128 : dist);
;             v[f][i] = ok ? s[f][i] + btab[di * 16 + H] : -1e30f;
;         }
; }
	v_lshl_add_u32 v255, v251, 6, v177
	v_add_u32_e32 v255, 0xfffff740, v255
	ds_read_b32 v232, v255 offset:2496
	ds_read_b32 v233, v255 offset:2432
	ds_read_b32 v234, v255 offset:2368
	ds_read_b32 v235, v255 offset:2304
	ds_read_b32 v236, v255 offset:2240
	ds_read_b32 v237, v255 offset:2176
	ds_read_b32 v238, v255 offset:2112
	ds_read_b32 v239, v255 offset:2048
	ds_read_b32 v240, v255 offset:448
	ds_read_b32 v241, v255 offset:384
	ds_read_b32 v242, v255 offset:320
	ds_read_b32 v243, v255 offset:256
	ds_read_b32 v244, v255 offset:192
	ds_read_b32 v245, v255 offset:128
	ds_read_b32 v246, v255 offset:64
	ds_read_b32 v247, v255 offset:0
	s_branch .Lsel_edge_co1
.Lsel_edge_cl1:
	v_add_u32_e32 v255, 4, v251
	v_min_u32_e32 v255, 0x80, v255
	v_lshl_add_u32 v232, v255, 6, v177
	ds_read_b32 v232, v232
	v_add_u32_e32 v255, 3, v251
	v_min_u32_e32 v255, 0x80, v255
	v_lshl_add_u32 v233, v255, 6, v177
	ds_read_b32 v233, v233
	v_add_u32_e32 v255, 2, v251
	v_min_u32_e32 v255, 0x80, v255
	v_lshl_add_u32 v234, v255, 6, v177
	ds_read_b32 v234, v234
	v_add_u32_e32 v255, 1, v251
	v_min_u32_e32 v255, 0x80, v255
	v_lshl_add_u32 v235, v255, 6, v177
	ds_read_b32 v235, v235
	v_add_u32_e32 v255, 0, v251
	v_min_u32_e32 v255, 0x80, v255
	v_lshl_add_u32 v236, v255, 6, v177
	ds_read_b32 v236, v236
	v_add_u32_e32 v255, -1, v251
	v_min_u32_e32 v255, 0x80, v255
	v_lshl_add_u32 v237, v255, 6, v177
	ds_read_b32 v237, v237
	v_add_u32_e32 v255, -2, v251
	v_min_u32_e32 v255, 0x80, v255
	v_lshl_add_u32 v238, v255, 6, v177
	ds_read_b32 v238, v238
	v_add_u32_e32 v255, -3, v251
	v_min_u32_e32 v255, 0x80, v255
	v_lshl_add_u32 v239, v255, 6, v177
	ds_read_b32 v239, v239
	v_add_u32_e32 v255, 0xffffffe4, v251
	v_min_u32_e32 v255, 0x80, v255
	v_lshl_add_u32 v240, v255, 6, v177
	ds_read_b32 v240, v240
	v_add_u32_e32 v255, 0xffffffe3, v251
	v_min_u32_e32 v255, 0x80, v255
	v_lshl_add_u32 v241, v255, 6, v177
	ds_read_b32 v241, v241
	v_add_u32_e32 v255, 0xffffffe2, v251
	v_min_u32_e32 v255, 0x80, v255
	v_lshl_add_u32 v242, v255, 6, v177
	ds_read_b32 v242, v242
	v_add_u32_e32 v255, 0xffffffe1, v251
	v_min_u32_e32 v255, 0x80, v255
	v_lshl_add_u32 v243, v255, 6, v177
	ds_read_b32 v243, v243
	v_add_u32_e32 v255, 0xffffffe0, v251
	v_min_u32_e32 v255, 0x80, v255
	v_lshl_add_u32 v244, v255, 6, v177
	ds_read_b32 v244, v244
	v_add_u32_e32 v255, 0xffffffdf, v251
	v_min_u32_e32 v255, 0x80, v255
	v_lshl_add_u32 v245, v255, 6, v177
	ds_read_b32 v245, v245
	v_add_u32_e32 v255, 0xffffffde, v251
	v_min_u32_e32 v255, 0x80, v255
	v_lshl_add_u32 v246, v255, 6, v177
	ds_read_b32 v246, v246
	v_add_u32_e32 v255, 0xffffffdd, v251
	v_min_u32_e32 v255, 0x80, v255
	v_lshl_add_u32 v247, v255, 6, v177
	ds_read_b32 v247, v247
; __device__ __forceinline__ void logits(float (&v)[4][4], const f32x4 (&s)[4], int tq, int kpos0, int kstride, int fq, int H, const float* btab, float farb, bool use_tab, int wl) {
; #pragma unroll
;     for (int f = 0; f < 4; ++f)
; #pragma unroll
;         for (int i = 0; i < 4; ++i) {
;             const int kk = 32 * (f >> 1) + 8 * fq + 4 * (f & 1) + i;
;             const int dist = tq - (kpos0 + kstride * kk);
;             const bool ok = dist >= 0 && dist < wl;
;             const int di = dist < 0 ? 0 : (dist > 128 ? 128 : dist);
;             v[f][i] = ok ? s[f][i] + btab[di * 16 + H] : -1e30f;
;         }
; }
; template <int CGM> ...
;     ...
;         f32x4 s[4]; qk(s, kf, q[cg_], 0.f); logits(v[cg_], s, tq[cg_], key0, 1, fq, H, btab, 0.f, true, wl);
;         float mx = red_max4(max16(v[cg_])); if (!selq[cg_]) mx = -1e30f; mnew[cg_] = fmaxf(m[cg_], mx);
;     }
;     if (__any(mnew[0] > m[0] || mnew[1] > m[1])) {
; #pragma unroll
;         for (int cg_ = 0; cg_ < 2; ++cg_) if ((CGM >> cg_) & 1) {
;             const float sc = __builtin_amdgcn_exp2f(m[cg_] - mnew[cg_]); l[cg_] *= sc; m[cg_] = mnew[cg_];
; #pragma unroll
;             for (int df = 0; df < 4; ++df) o[cg_][df] *= sc;
;         }
.Lsel_edge_co1:
	v_add_u32_e32 v248, 4, v251
	v_cmp_gt_u32_e64 s[6:7], s98, v248
	v_add_u32_e32 v249, 3, v251
	v_cmp_gt_u32_e64 s[12:13], s98, v249
	v_add_u32_e32 v250, 2, v251
	v_cmp_gt_u32_e64 s[14:15], s98, v250
	s_waitcnt lgkmcnt(15)
	v_add_f32_e32 v108, v108, v232
	v_cndmask_b32_e64 v108, v148, v108, s[6:7]
	v_add_u32_e32 v248, 1, v251
	v_cmp_gt_u32_e64 s[6:7], s98, v248
	s_waitcnt lgkmcnt(14)
	v_add_f32_e32 v109, v109, v233
	v_cndmask_b32_e64 v109, v148, v109, s[12:13]
	v_add_u32_e32 v249, 0, v251
	v_cmp_gt_u32_e64 s[12:13], s98, v249
	s_waitcnt lgkmcnt(13)
	v_add_f32_e32 v110, v110, v234
	v_cndmask_b32_e64 v110, v148, v110, s[14:15]
	v_add_u32_e32 v250, -1, v251
	v_cmp_gt_u32_e64 s[14:15], s98, v250
	s_waitcnt lgkmcnt(12)
	v_add_f32_e32 v111, v111, v235
	v_cndmask_b32_e64 v111, v148, v111, s[6:7]
	v_add_u32_e32 v248, -2, v251
	v_cmp_gt_u32_e64 s[6:7], s98, v248
	s_waitcnt lgkmcnt(11)
	v_add_f32_e32 v112, v112, v236
	v_cndmask_b32_e64 v112, v148, v112, s[12:13]
	v_add_u32_e32 v249, -3, v251
	v_cmp_gt_u32_e64 s[12:13], s98, v249
	s_waitcnt lgkmcnt(10)
	v_add_f32_e32 v113, v113, v237
	v_cndmask_b32_e64 v113, v148, v113, s[14:15]
	v_add_u32_e32 v250, 0xffffffe4, v251
	v_cmp_gt_u32_e64 s[14:15], s98, v250
	s_waitcnt lgkmcnt(9)
	v_add_f32_e32 v114, v114, v238
	v_cndmask_b32_e64 v114, v148, v114, s[6:7]
	v_add_u32_e32 v248, 0xffffffe3, v251
	v_cmp_gt_u32_e64 s[6:7], s98, v248
	s_waitcnt lgkmcnt(8)
	v_add_f32_e32 v115, v115, v239
	v_cndmask_b32_e64 v115, v148, v115, s[12:13]
	v_add_u32_e32 v249, 0xffffffe2, v251
	v_cmp_gt_u32_e64 s[12:13], s98, v249
	s_waitcnt lgkmcnt(7)
	v_add_f32_e32 v116, v116, v240
	v_cndmask_b32_e64 v116, v148, v116, s[14:15]
	v_add_u32_e32 v250, 0xffffffe1, v251
	v_cmp_gt_u32_e64 s[14:15], s98, v250
	s_waitcnt lgkmcnt(6)
	v_add_f32_e32 v117, v117, v241
	v_cndmask_b32_e64 v117, v148, v117, s[6:7]
	v_add_u32_e32 v248, 0xffffffe0, v251
	v_cmp_gt_u32_e64 s[6:7], s98, v248
	s_waitcnt lgkmcnt(5)
	v_add_f32_e32 v118, v118, v242
	v_cndmask_b32_e64 v118, v148, v118, s[12:13]
	v_add_u32_e32 v249, 0xffffffdf, v251
	v_cmp_gt_u32_e64 s[12:13], s98, v249
	s_waitcnt lgkmcnt(4)
	v_add_f32_e32 v119, v119, v243
	v_cndmask_b32_e64 v119, v148, v119, s[14:15]
	v_add_u32_e32 v250, 0xffffffde, v251
	v_cmp_gt_u32_e64 s[14:15], s98, v250
	s_waitcnt lgkmcnt(3)
	v_add_f32_e32 v120, v120, v244
	v_cndmask_b32_e64 v120, v148, v120, s[6:7]
	v_add_u32_e32 v248, 0xffffffdd, v251
	v_cmp_gt_u32_e64 s[6:7], s98, v248
	s_waitcnt lgkmcnt(2)
	v_add_f32_e32 v121, v121, v245
	v_cndmask_b32_e64 v121, v148, v121, s[12:13]
	s_waitcnt lgkmcnt(1)
	v_add_f32_e32 v122, v122, v246
	v_cndmask_b32_e64 v122, v148, v122, s[14:15]
	s_waitcnt lgkmcnt(0)
	v_add_f32_e32 v123, v123, v247
	v_cndmask_b32_e64 v123, v148, v123, s[6:7]
	ds_read_b128 v[88:91], v143 offset:8192
	ds_read_b128 v[80:83], v143 offset:8704
	ds_read_b128 v[72:75], v143 offset:12288
	ds_read_b128 v[60:63], v143 offset:12800
	ds_read_b128 v[84:87], v142 offset:8192
	ds_read_b128 v[76:79], v142 offset:8704
	ds_read_b128 v[68:71], v142 offset:12288
	ds_read_b128 v[64:67], v142 offset:12800
	v_max3_f32 v128, v92, v93, v94
	v_max3_f32 v129, v95, v96, v97
	v_max3_f32 v130, v98, v99, v100
	v_max3_f32 v131, v101, v102, v103
	v_max3_f32 v144, v108, v109, v110
	v_max3_f32 v145, v111, v112, v113
	v_max3_f32 v146, v114, v115, v116
	v_max3_f32 v147, v117, v118, v119
	v_max3_f32 v128, v128, v104, v105
	v_max3_f32 v129, v129, v106, v107
	v_max3_f32 v144, v144, v120, v121
	v_max3_f32 v145, v145, v122, v123
	v_max3_f32 v128, v128, v129, v130
	v_max3_f32 v144, v144, v145, v146
	v_max_f32_e32 v128, v128, v131
	v_max_f32_e32 v144, v144, v147
	v_mov_b32_e32 v129, v128
	v_mov_b32_e32 v145, v144
	s_nop 1
	v_permlane16_swap_b32_e32 v128, v129
	v_permlane16_swap_b32_e32 v144, v145
	v_max_f32_e32 v128, v128, v129
	v_max_f32_e32 v144, v144, v145
	v_mov_b32_e32 v129, v128
	v_mov_b32_e32 v145, v144
	s_nop 1
	v_permlane32_swap_b32_e32 v128, v129
	v_permlane32_swap_b32_e32 v144, v145
	v_max_f32_e32 v128, v128, v129
	v_max_f32_e32 v144, v144, v145
	v_cndmask_b32_e64 v128, v148, v128, s[10:11]
	v_cndmask_b32_e64 v144, v148, v144, s[8:9]
	v_max_f32_e32 v129, v124, v128
	v_max_f32_e32 v145, v125, v144
	v_cmp_gt_f32_e32 vcc, v129, v124
	v_cmp_gt_f32_e64 s[6:7], v145, v125
	s_or_b64 vcc, vcc, s[6:7]
	s_cbranch_vccz .Lsel_edge_nors
	v_sub_f32_e32 v128, v124, v129
	v_sub_f32_e32 v146, v125, v145
	v_exp_f32_e32 v128, v128
	v_exp_f32_e32 v146, v146
	v_mov_b32_e32 v124, v129
	v_mov_b32_e32 v125, v145
	v_mul_f32_e32 v127, v127, v128
	v_pk_mul_f32 v[56:57], v[56:57], v[128:129] op_sel_hi:[1,0]
	v_pk_mul_f32 v[58:59], v[58:59], v[128:129] op_sel_hi:[1,0]
	v_pk_mul_f32 v[52:53], v[52:53], v[128:129] op_sel_hi:[1,0]
	v_pk_mul_f32 v[54:55], v[54:55], v[128:129] op_sel_hi:[1,0]
	v_pk_mul_f32 v[48:49], v[48:49], v[128:129] op_sel_hi:[1,0]
	v_pk_mul_f32 v[50:51], v[50:51], v[128:129] op_sel_hi:[1,0]
	v_pk_mul_f32 v[44:45], v[44:45], v[128:129] op_sel_hi:[1,0]
	v_pk_mul_f32 v[46:47], v[46:47], v[128:129] op_sel_hi:[1,0]
	v_mul_f32_e32 v126, v126, v146
	v_pk_mul_f32 v[40:41], v[40:41], v[146:147] op_sel_hi:[1,0]
	v_pk_mul_f32 v[42:43], v[42:43], v[146:147] op_sel_hi:[1,0]
	v_pk_mul_f32 v[28:29], v[28:29], v[146:147] op_sel_hi:[1,0]
	v_pk_mul_f32 v[30:31], v[30:31], v[146:147] op_sel_hi:[1,0]
	v_pk_mul_f32 v[24:25], v[24:25], v[146:147] op_sel_hi:[1,0]
	v_pk_mul_f32 v[26:27], v[26:27], v[146:147] op_sel_hi:[1,0]
	v_pk_mul_f32 v[20:21], v[20:21], v[146:147] op_sel_hi:[1,0]
	v_pk_mul_f32 v[22:23], v[22:23], v[146:147] op_sel_hi:[1,0]

; __device__ __forceinline__ void logits(float (&v)[4][4], const f32x4 (&s)[4], int tq, int kpos0, int kstride, int fq, int H, const float* btab, float farb, bool use_tab, int wl) {
; #pragma unroll
;     for (int f = 0; f < 4; ++f)
; #pragma unroll
;         for (int i = 0; i < 4; ++i) {
;             const int kk = 32 * (f >> 1) + 8 * fq + 4 * (f & 1) + i;
;             const int dist = tq - (kpos0 + kstride * kk);
;             const bool ok = dist >= 0 && dist < wl;
;             const int di = dist < 0 ? 0 : (dist > 128 ? 128 : dist);
;             v[f][i] = ok ? s[f][i] + btab[di * 16 + H] : -1e30f;
;         }
; }
; template <int CGM> ...
;     float v[2][4][4]; float mnew[2] = {m[0], m[1]};
; #pragma unroll
;     for (int cg_ = 0; cg_ < 2; ++cg_) if ((CGM >> cg_) & 1) {
;         f32x4 s[4]; qk(s, kf, q[cg_], 0.f); logits(v[cg_], s, tq[cg_], key0, 1, fq, H, btab, 0.f, true, wl);
.Lwin_edge:
	v_add_u32_e32 v251, s4, v179
	s_waitcnt lgkmcnt(7)
	v_mfma_f32_16x16x32_bf16 v[116:119], v[80:83], v[2:5], 0
	v_mfma_f32_16x16x32_bf16 v[136:139], v[80:83], v[10:13], 0
	s_waitcnt lgkmcnt(6)
	v_mfma_f32_16x16x32_bf16 v[120:123], v[72:75], v[2:5], 0
	v_mfma_f32_16x16x32_bf16 v[140:143], v[72:75], v[10:13], 0
	s_waitcnt lgkmcnt(5)
	v_mfma_f32_16x16x32_bf16 v[116:119], v[76:79], v[6:9], v[116:119]
	v_mfma_f32_16x16x32_bf16 v[136:139], v[76:79], v[14:17], v[136:139]
	s_waitcnt lgkmcnt(4)
	v_mfma_f32_16x16x32_bf16 v[120:123], v[68:71], v[6:9], v[120:123]
	v_mfma_f32_16x16x32_bf16 v[140:143], v[68:71], v[14:17], v[140:143]
	s_waitcnt lgkmcnt(3)
	v_mfma_f32_16x16x32_bf16 v[124:127], v[60:63], v[2:5], 0
	v_mfma_f32_16x16x32_bf16 v[144:147], v[60:63], v[10:13], 0
	s_waitcnt lgkmcnt(2)
	v_mfma_f32_16x16x32_bf16 v[132:135], v[56:59], v[2:5], 0
	v_mfma_f32_16x16x32_bf16 v[184:187], v[56:59], v[10:13], 0
	s_waitcnt lgkmcnt(1)
	v_mfma_f32_16x16x32_bf16 v[124:127], v[64:67], v[6:9], v[124:127]
	v_mfma_f32_16x16x32_bf16 v[144:147], v[64:67], v[14:17], v[144:147]
	s_waitcnt lgkmcnt(0)
	v_mfma_f32_16x16x32_bf16 v[132:135], v[52:55], v[6:9], v[132:135]
	v_mfma_f32_16x16x32_bf16 v[184:187], v[52:55], v[14:17], v[184:187]
	s_add_i32 s99, s0, -1
	s_cmp_ge_i32 s38, s99
	s_cbranch_scc0 .Lwin_edge_cl0
	v_lshl_add_u32 v255, v251, 6, v177
	v_add_u32_e32 v255, 0xfffff640, v255
	ds_read_b32 v232, v255 offset:2496
	ds_read_b32 v233, v255 offset:2432
	ds_read_b32 v234, v255 offset:2368
	ds_read_b32 v235, v255 offset:2304
	ds_read_b32 v236, v255 offset:2240
	ds_read_b32 v237, v255 offset:2176
	ds_read_b32 v238, v255 offset:2112
	ds_read_b32 v239, v255 offset:2048
	ds_read_b32 v240, v255 offset:448
	ds_read_b32 v241, v255 offset:384
	ds_read_b32 v242, v255 offset:320
	ds_read_b32 v243, v255 offset:256
	ds_read_b32 v244, v255 offset:192
	ds_read_b32 v245, v255 offset:128
	ds_read_b32 v246, v255 offset:64
	ds_read_b32 v247, v255 offset:0
	s_branch .Lwin_edge_co0

; __device__ __forceinline__ void logits(float (&v)[4][4], const f32x4 (&s)[4], int tq, int kpos0, int kstride, int fq, int H, const float* btab, float farb, bool use_tab, int wl) {
; #pragma unroll
;     for (int f = 0; f < 4; ++f)
; #pragma unroll
;         for (int i = 0; i < 4; ++i) {
;             const int kk = 32 * (f >> 1) + 8 * fq + 4 * (f & 1) + i;
;             const int dist = tq - (kpos0 + kstride * kk);
;             const bool ok = dist >= 0 && dist < wl;
;             const int di = dist < 0 ? 0 : (dist > 128 ? 128 : dist);
;             v[f][i] = ok ? s[f][i] + btab[di * 16 + H] : -1e30f;
;         }
; }
.Lwin_edge_co0:
	v_add_u32_e32 v248, 0, v251
	v_cmp_gt_u32_e64 s[8:9], s92, v248
	v_add_u32_e32 v249, -1, v251
	v_cmp_gt_u32_e64 s[10:11], s92, v249
	v_add_u32_e32 v250, -2, v251
	v_cmp_gt_u32_e64 s[12:13], s92, v250
	s_waitcnt lgkmcnt(15)
	v_add_f32_e32 v116, v116, v232
	v_cndmask_b32_e64 v116, v148, v116, s[8:9]
	v_add_u32_e32 v248, -3, v251
	v_cmp_gt_u32_e64 s[8:9], s92, v248
	s_waitcnt lgkmcnt(14)
	v_add_f32_e32 v117, v117, v233
	v_cndmask_b32_e64 v117, v148, v117, s[10:11]
	v_add_u32_e32 v249, -4, v251
	v_cmp_gt_u32_e64 s[10:11], s92, v249
	s_waitcnt lgkmcnt(13)
	v_add_f32_e32 v118, v118, v234
	v_cndmask_b32_e64 v118, v148, v118, s[12:13]
	v_add_u32_e32 v250, -5, v251
	v_cmp_gt_u32_e64 s[12:13], s92, v250
	s_waitcnt lgkmcnt(12)
	v_add_f32_e32 v119, v119, v235
	v_cndmask_b32_e64 v119, v148, v119, s[8:9]
	v_add_u32_e32 v248, -6, v251
	v_cmp_gt_u32_e64 s[8:9], s92, v248
	s_waitcnt lgkmcnt(11)
	v_add_f32_e32 v120, v120, v236
	v_cndmask_b32_e64 v120, v148, v120, s[10:11]
	v_add_u32_e32 v249, -7, v251
	v_cmp_gt_u32_e64 s[10:11], s92, v249
	s_waitcnt lgkmcnt(10)
	v_add_f32_e32 v121, v121, v237
	v_cndmask_b32_e64 v121, v148, v121, s[12:13]
	v_add_u32_e32 v250, 0xffffffe0, v251
	v_cmp_gt_u32_e64 s[12:13], s92, v250
	s_waitcnt lgkmcnt(9)
	v_add_f32_e32 v122, v122, v238
	v_cndmask_b32_e64 v122, v148, v122, s[8:9]
	v_add_u32_e32 v248, 0xffffffdf, v251
	v_cmp_gt_u32_e64 s[8:9], s92, v248
	s_waitcnt lgkmcnt(8)
	v_add_f32_e32 v123, v123, v239
	v_cndmask_b32_e64 v123, v148, v123, s[10:11]
	v_add_u32_e32 v249, 0xffffffde, v251
	v_cmp_gt_u32_e64 s[10:11], s92, v249
	s_waitcnt lgkmcnt(7)
	v_add_f32_e32 v124, v124, v240
	v_cndmask_b32_e64 v124, v148, v124, s[12:13]
	v_add_u32_e32 v250, 0xffffffdd, v251
	v_cmp_gt_u32_e64 s[12:13], s92, v250
	s_waitcnt lgkmcnt(6)
	v_add_f32_e32 v125, v125, v241
	v_cndmask_b32_e64 v125, v148, v125, s[8:9]
	v_add_u32_e32 v248, 0xffffffdc, v251
	v_cmp_gt_u32_e64 s[8:9], s92, v248
	s_waitcnt lgkmcnt(5)
	v_add_f32_e32 v126, v126, v242
	v_cndmask_b32_e64 v126, v148, v126, s[10:11]
	v_add_u32_e32 v249, 0xffffffdb, v251
	v_cmp_gt_u32_e64 s[10:11], s92, v249
	s_waitcnt lgkmcnt(4)
	v_add_f32_e32 v127, v127, v243
	v_cndmask_b32_e64 v127, v148, v127, s[12:13]
	v_add_u32_e32 v250, 0xffffffda, v251
	v_cmp_gt_u32_e64 s[12:13], s92, v250
	s_waitcnt lgkmcnt(3)
	v_add_f32_e32 v132, v132, v244
	v_cndmask_b32_e64 v132, v148, v132, s[8:9]
	v_add_u32_e32 v248, 0xffffffd9, v251
	v_cmp_gt_u32_e64 s[8:9], s92, v248
	s_waitcnt lgkmcnt(2)
	v_add_f32_e32 v133, v133, v245
	v_cndmask_b32_e64 v133, v148, v133, s[10:11]
	s_waitcnt lgkmcnt(1)
	v_add_f32_e32 v134, v134, v246
	v_cndmask_b32_e64 v134, v148, v134, s[12:13]
	s_waitcnt lgkmcnt(0)
	v_add_f32_e32 v135, v135, v247
	v_cndmask_b32_e64 v135, v148, v135, s[8:9]
	s_add_i32 s99, s0, -1
	s_cmp_ge_i32 s38, s99
	s_cbranch_scc0 .Lwin_edge_cl1
	v_lshl_add_u32 v255, v251, 6, v177
	v_add_u32_e32 v255, 0xfffff740, v255
	ds_read_b32 v232, v255 offset:2496
	ds_read_b32 v233, v255 offset:2432
	ds_read_b32 v234, v255 offset:2368
	ds_read_b32 v235, v255 offset:2304
	ds_read_b32 v236, v255 offset:2240
	ds_read_b32 v237, v255 offset:2176
	ds_read_b32 v238, v255 offset:2112
	ds_read_b32 v239, v255 offset:2048
	ds_read_b32 v240, v255 offset:448
	ds_read_b32 v241, v255 offset:384
	ds_read_b32 v242, v255 offset:320
	ds_read_b32 v243, v255 offset:256
	ds_read_b32 v244, v255 offset:192
	ds_read_b32 v245, v255 offset:128
	ds_read_b32 v246, v255 offset:64
	ds_read_b32 v247, v255 offset:0
	s_branch .Lwin_edge_co1

; __device__ __forceinline__ void logits(float (&v)[4][4], const f32x4 (&s)[4], int tq, int kpos0, int kstride, int fq, int H, const float* btab, float farb, bool use_tab, int wl) {
; #pragma unroll
;     for (int f = 0; f < 4; ++f)
; #pragma unroll
;         for (int i = 0; i < 4; ++i) {
;             const int kk = 32 * (f >> 1) + 8 * fq + 4 * (f & 1) + i;
;             const int dist = tq - (kpos0 + kstride * kk);
;             const bool ok = dist >= 0 && dist < wl;
;             const int di = dist < 0 ? 0 : (dist > 128 ? 128 : dist);
;             v[f][i] = ok ? s[f][i] + btab[di * 16 + H] : -1e30f;
;         }
; }
; template <int CGM> ...
;     ...
;         f32x4 s[4]; qk(s, kf, q[cg_], 0.f); logits(v[cg_], s, tq[cg_], key0, 1, fq, H, btab, 0.f, true, wl);
;         float mx = red_max4(max16(v[cg_])); if (!selq[cg_]) mx = -1e30f; mnew[cg_] = fmaxf(m[cg_], mx);
;     }
;     if (__any(mnew[0] > m[0] || mnew[1] > m[1])) {
; #pragma unroll
;         for (int cg_ = 0; cg_ < 2; ++cg_) if ((CGM >> cg_) & 1) {
;             const float sc = __builtin_amdgcn_exp2f(m[cg_] - mnew[cg_]); l[cg_] *= sc; m[cg_] = mnew[cg_];
; #pragma unroll
;             for (int df = 0; df < 4; ++df) o[cg_][df] *= sc;
;         }
.Lwin_edge_co1:
	v_add_u32_e32 v248, 4, v251
	v_cmp_gt_u32_e64 s[8:9], s92, v248
	v_add_u32_e32 v249, 3, v251
	v_cmp_gt_u32_e64 s[10:11], s92, v249
	v_add_u32_e32 v250, 2, v251
	v_cmp_gt_u32_e64 s[12:13], s92, v250
	s_waitcnt lgkmcnt(15)
	v_add_f32_e32 v136, v136, v232
	v_cndmask_b32_e64 v136, v148, v136, s[8:9]
	v_add_u32_e32 v248, 1, v251
	v_cmp_gt_u32_e64 s[8:9], s92, v248
	s_waitcnt lgkmcnt(14)
	v_add_f32_e32 v137, v137, v233
	v_cndmask_b32_e64 v137, v148, v137, s[10:11]
	v_add_u32_e32 v249, 0, v251
	v_cmp_gt_u32_e64 s[10:11], s92, v249
	s_waitcnt lgkmcnt(13)
	v_add_f32_e32 v138, v138, v234
	v_cndmask_b32_e64 v138, v148, v138, s[12:13]
	v_add_u32_e32 v250, -1, v251
	v_cmp_gt_u32_e64 s[12:13], s92, v250
	s_waitcnt lgkmcnt(12)
	v_add_f32_e32 v139, v139, v235
	v_cndmask_b32_e64 v139, v148, v139, s[8:9]
	v_add_u32_e32 v248, -2, v251
	v_cmp_gt_u32_e64 s[8:9], s92, v248
	s_waitcnt lgkmcnt(11)
	v_add_f32_e32 v140, v140, v236
	v_cndmask_b32_e64 v140, v148, v140, s[10:11]
	v_add_u32_e32 v249, -3, v251
	v_cmp_gt_u32_e64 s[10:11], s92, v249
	s_waitcnt lgkmcnt(10)
	v_add_f32_e32 v141, v141, v237
	v_cndmask_b32_e64 v141, v148, v141, s[12:13]
	v_add_u32_e32 v250, 0xffffffe4, v251
	v_cmp_gt_u32_e64 s[12:13], s92, v250
	s_waitcnt lgkmcnt(9)
	v_add_f32_e32 v142, v142, v238
	v_cndmask_b32_e64 v142, v148, v142, s[8:9]
	v_add_u32_e32 v248, 0xffffffe3, v251
	v_cmp_gt_u32_e64 s[8:9], s92, v248
	s_waitcnt lgkmcnt(8)
	v_add_f32_e32 v143, v143, v239
	v_cndmask_b32_e64 v143, v148, v143, s[10:11]
	v_add_u32_e32 v249, 0xffffffe2, v251
	v_cmp_gt_u32_e64 s[10:11], s92, v249
	s_waitcnt lgkmcnt(7)
	v_add_f32_e32 v144, v144, v240
	v_cndmask_b32_e64 v144, v148, v144, s[12:13]
	v_add_u32_e32 v250, 0xffffffe1, v251
	v_cmp_gt_u32_e64 s[12:13], s92, v250
	s_waitcnt lgkmcnt(6)
	v_add_f32_e32 v145, v145, v241
	v_cndmask_b32_e64 v145, v148, v145, s[8:9]
	v_add_u32_e32 v248, 0xffffffe0, v251
	v_cmp_gt_u32_e64 s[8:9], s92, v248
	s_waitcnt lgkmcnt(5)
	v_add_f32_e32 v146, v146, v242
	v_cndmask_b32_e64 v146, v148, v146, s[10:11]
	v_add_u32_e32 v249, 0xffffffdf, v251
	v_cmp_gt_u32_e64 s[10:11], s92, v249
	s_waitcnt lgkmcnt(4)
	v_add_f32_e32 v147, v147, v243
	v_cndmask_b32_e64 v147, v148, v147, s[12:13]
	v_add_u32_e32 v250, 0xffffffde, v251
	v_cmp_gt_u32_e64 s[12:13], s92, v250
	s_waitcnt lgkmcnt(3)
	v_add_f32_e32 v184, v184, v244
	v_cndmask_b32_e64 v184, v148, v184, s[8:9]
	v_add_u32_e32 v248, 0xffffffdd, v251
	v_cmp_gt_u32_e64 s[8:9], s92, v248
	s_waitcnt lgkmcnt(2)
	v_add_f32_e32 v185, v185, v245
	v_cndmask_b32_e64 v185, v148, v185, s[10:11]
	s_waitcnt lgkmcnt(1)
	v_add_f32_e32 v186, v186, v246
	v_cndmask_b32_e64 v186, v148, v186, s[12:13]
	s_waitcnt lgkmcnt(0)
	v_add_f32_e32 v187, v187, v247
	v_cndmask_b32_e64 v187, v148, v187, s[8:9]
	ds_read_b128 v[80:83], v149 offset:8192
	ds_read_b128 v[72:75], v149 offset:8704
	ds_read_b128 v[60:63], v149 offset:12288
	ds_read_b128 v[56:59], v149 offset:12800
	ds_read_b128 v[76:79], v182 offset:8192
	ds_read_b128 v[68:71], v182 offset:8704
	ds_read_b128 v[64:67], v182 offset:12288
	ds_read_b128 v[52:55], v182 offset:12800
	v_max3_f32 v188, v116, v117, v118
	v_max3_f32 v189, v119, v120, v121
	v_max3_f32 v190, v122, v123, v124
	v_max3_f32 v191, v125, v126, v127
	v_max3_f32 v192, v136, v137, v138
	v_max3_f32 v193, v139, v140, v141
	v_max3_f32 v194, v142, v143, v144
	v_max3_f32 v195, v145, v146, v147
	v_max3_f32 v188, v188, v132, v133
	v_max3_f32 v189, v189, v134, v135
	v_max3_f32 v192, v192, v184, v185
	v_max3_f32 v193, v193, v186, v187
	v_max3_f32 v188, v188, v189, v190
	v_max3_f32 v192, v192, v193, v194
	v_max_f32_e32 v188, v188, v191
	v_max_f32_e32 v192, v192, v195
	v_mov_b32_e32 v189, v188
	v_mov_b32_e32 v193, v192
	s_nop 1
	v_permlane16_swap_b32_e32 v188, v189
	v_permlane16_swap_b32_e32 v192, v193
	v_max_f32_e32 v188, v188, v189
	v_max_f32_e32 v192, v192, v193
	v_mov_b32_e32 v189, v188
	v_mov_b32_e32 v193, v192
	s_nop 1
	v_permlane32_swap_b32_e32 v188, v189
	v_permlane32_swap_b32_e32 v192, v193
	v_max_f32_e32 v188, v188, v189
	v_max_f32_e32 v192, v192, v193
	v_max_f32_e32 v189, v156, v188
	v_max_f32_e32 v193, v157, v192
	v_cmp_gt_f32_e32 vcc, v189, v156
	v_cmp_gt_f32_e64 s[8:9], v193, v157
	s_or_b64 vcc, vcc, s[8:9]
	s_cbranch_vccz .Lwin_edge_nors
	v_sub_f32_e32 v188, v156, v189
	v_sub_f32_e32 v194, v157, v193
	v_exp_f32_e32 v188, v188
	v_exp_f32_e32 v194, v194
	v_mov_b32_e32 v156, v189
	v_mov_b32_e32 v157, v193
	v_mul_f32_e32 v155, v155, v188
	v_pk_mul_f32 v[48:49], v[48:49], v[188:189] op_sel_hi:[1,0]
	v_pk_mul_f32 v[50:51], v[50:51], v[188:189] op_sel_hi:[1,0]
	v_pk_mul_f32 v[40:41], v[40:41], v[188:189] op_sel_hi:[1,0]
	v_pk_mul_f32 v[42:43], v[42:43], v[188:189] op_sel_hi:[1,0]
	v_pk_mul_f32 v[32:33], v[32:33], v[188:189] op_sel_hi:[1,0]
	v_pk_mul_f32 v[34:35], v[34:35], v[188:189] op_sel_hi:[1,0]
	v_pk_mul_f32 v[24:25], v[24:25], v[188:189] op_sel_hi:[1,0]
	v_pk_mul_f32 v[26:27], v[26:27], v[188:189] op_sel_hi:[1,0]
	v_mul_f32_e32 v154, v154, v194
	v_pk_mul_f32 v[44:45], v[44:45], v[194:195] op_sel_hi:[1,0]
	v_pk_mul_f32 v[46:47], v[46:47], v[194:195] op_sel_hi:[1,0]
	v_pk_mul_f32 v[36:37], v[36:37], v[194:195] op_sel_hi:[1,0]
	v_pk_mul_f32 v[38:39], v[38:39], v[194:195] op_sel_hi:[1,0]
	v_pk_mul_f32 v[28:29], v[28:29], v[194:195] op_sel_hi:[1,0]
	v_pk_mul_f32 v[30:31], v[30:31], v[194:195] op_sel_hi:[1,0]
	v_pk_mul_f32 v[20:21], v[20:21], v[194:195] op_sel_hi:[1,0]
	v_pk_mul_f32 v[22:23], v[22:23], v[194:195] op_sel_hi:[1,0]
